# GEMM1 kind-2 R stores merged into full 128-B-line stores via DPP row_ror:8 + select (on top of B-column permutation and widened mixer stores)
# baseline (speedup 1.0000x reference)
; #define LAS __attribute__((address_space(3)))
; #define ZERO_ACC(acc) do { _Pragma("unroll") for (int _a = 0; _a < 2; ++_a) _Pragma("unroll") for (int _b = 0; _b < 2; ++_b) _Pragma("unroll") for (int _m = 0; _m < 4; ++_m) _Pragma("unroll") for (int _n = 0; _n < 2; ++_n) \
;     (acc)[_a][_b][_m][_n] = (f32x4){0.f, 0.f, 0.f, 0.f}; } while (0)
; template <int PH> __global__ void __launch_bounds__(512, 2) fwd(Params p) {
;     ...
;     if (PH < 0) { volatile LAS unsigned* st = (volatile LAS unsigned*)((LAS unsigned char*)lds + LDS_MAIN); even = st[2] != 0u; if (even) vid = (int)(xb.x + 8u * st[3]); }
;     if (PH < 0 || PH == 1) {
;         pg8::Gemm g; g.A = (const bf16_t*)(p.ws + WS_OPS); g.Bt = g.A; g.K = 1024;
;         pg8::ProjOrder S; S.G = gridDim.x; S.c = vid;
;         pg8::EpiProj E; E.qk = (bf16_t*)(p.ws + WS_QK); E.vt = (bf16_t*)(p.ws + WS_VT); E.r = (bf16_t*)(p.ws + WS_R); E.mk = (bf16_t*)(p.ws + WS_MK); E.mvt = (bf16_t*)(p.ws + WS_MVT);
;         f32x4 acc[2][2][4][2]; ZERO_ACC(acc);
;         pg8::gemm_phase<pg8::EpiProj, pg8::ProjOrder, true>((LAS unsigned char*)lds, g, S, E, acc);
.LBB0_124:
	s_mov_b32 s100, 0xff00ff00
	s_mov_b32 s101, 0xff00ff00
	v_bfe_u32 v248, v179, 3, 1
	v_mul_u32_u24_e32 v250, 0x7fc0, v248
	v_sub_u32_e32 v248, 0xffffffc0, v250
	v_mov_b32_e32 v249, -1
	v_sub_u32_e32 v250, 0x7fc0, v250
	v_mov_b32_e32 v251, 0
	s_add_u32 s42, s0, 0x78
	s_addc_u32 s43, s1, 0
	v_mov_b32_e32 v8, v179
	s_cmpk_lt_i32 s2, 0x382
	s_cselect_b64 s[14:15], -1, 0
	s_cmpk_gt_i32 s2, 0x381
	v_readfirstlane_b32 s18, v8
	s_cbranch_scc1 .LBB0_137
	s_cmpk_gt_i32 s2, 0x380
	s_mov_b64 s[4:5], -1
	s_cbranch_scc0 .LBB0_127
	s_mov_b64 s[4:5], 0

; DI unsigned pk_bf16(float lo, float hi) { f32x2 v = {lo, hi}; bf2_t b = __builtin_convertvector(v, bf2_t); return __builtin_bit_cast(unsigned, b); }
; DI int pi32e(int r) { return (r & ~12) | ((r & 4) << 1) | ((r & 8) >> 1); }
;     DI void operator()(const f32x4 (&acc)[2][2][4][2], const Unit& u, int wr, int wc, int fr, int fq) const {
;     ...
;                 for (int bj = 0; bj < 2; ++bj) { const f32x4 v0 = acc[ai][bj][m][0] * sc, v1 = acc[ai][bj][m][1] * sc; const int col = col0 + bj * HALF;
;                     u32x4 w; w.x = pk_bf16(v0[0], v0[1]); w.y = pk_bf16(v0[2], v0[3]); w.z = pk_bf16(v1[0], v1[1]); w.w = pk_bf16(v1[2], v1[3]);
;                     bf16_t* dst;
;                     if (u.kind == 0) {
;                         const int isk = col >> 9, c = col & 511, rr = isk ? pi32e(row & 31) : (row & 31);
;                         dst = base + (size_t)isk * ((size_t)T * 512) + ((((size_t)(row >> 5) * 8 + (c >> 6)) * 4 + ((c & 63) >> 4)) * 64 + ((c >> 3) & 1) * 32 + rr) * 8;
;                     } else if (u.kind == 1) {
;                         dst = base + ((((size_t)(col >> 5) * 8 + (row >> 6)) * 4 + ((row & 63) >> 5) * 2 + ((col & 31) >> 4)) * 64 + ((col >> 3) & 1) * 32 + (row & 31)) * 8;
;                     } else dst = base + (size_t)row * ldc + col;
;                     *(u32x4*)dst = w; } }
.LBB0_187:
	s_cmp_eq_u32 s38, 0
	s_cselect_b64 s[54:55], -1, 0
	s_cmp_lt_i32 s37, 2
	s_cselect_b64 s[62:63], -1, 0
	s_and_b64 s[54:55], s[54:55], s[62:63]
	s_cmp_eq_u32 s38, 2
	s_cselect_b64 s[62:63], -1, 0
	s_cmp_eq_u32 s37, 3
	s_cselect_b64 s[72:73], -1, 0
	s_and_b64 s[62:63], s[62:63], s[72:73]
	s_or_b64 vcc, s[54:55], s[62:63]
	v_cndmask_b32_e32 v150, 1.0, v167, vcc
	v_mov_b32_e32 v151, v150
	v_pk_mul_f32 v[126:127], v[150:151], v[126:127] op_sel_hi:[0,1]
	v_pk_mul_f32 v[124:125], v[150:151], v[124:125] op_sel_hi:[0,1]
	v_pk_mul_f32 v[172:173], v[150:151], v[122:123] op_sel_hi:[0,1]
	v_pk_mul_f32 v[122:123], v[150:151], v[120:121] op_sel_hi:[0,1]
	s_or_b32 s23, s36, 32
	v_cvt_pk_bf16_f32 v120, v124, v125
	v_cvt_pk_bf16_f32 v121, v126, v127
	v_cvt_pk_bf16_f32 v122, v122, v123
	v_cvt_pk_bf16_f32 v123, v172, v173
	s_mov_b64 s[72:73], -1
	s_mov_b64 s[54:55], 0
	s_cmp_lt_i32 s38, 1
	s_mov_b64 s[62:63], 0
	s_cselect_b32 s32, 1, 0
	s_cmp_eq_u32 s38, 2
	s_cbranch_scc1 .Lk2a_0
	s_cmp_lg_u32 s32, 0
	global_store_dwordx4 v[160:161], v[120:123], off
	s_branch .Lk2c_0
.Lk2a_0:
	v_mov_b32_e32 v236, v120
	v_mov_b32_e32 v237, v121
	v_mov_b32_e32 v238, v122
	v_mov_b32_e32 v239, v123
	s_cmp_lg_u32 s32, 0
.Lk2c_0:
	s_cbranch_scc0 .LBB0_300
	s_and_b64 vcc, exec, s[72:73]
	s_cbranch_vccnz .LBB0_303

; DI unsigned pk_bf16(float lo, float hi) { f32x2 v = {lo, hi}; bf2_t b = __builtin_convertvector(v, bf2_t); return __builtin_bit_cast(unsigned, b); }
; DI int pi32e(int r) { return (r & ~12) | ((r & 4) << 1) | ((r & 8) >> 1); }
;     DI void operator()(const f32x4 (&acc)[2][2][4][2], const Unit& u, int wr, int wc, int fr, int fq) const {
;     ...
;                 for (int bj = 0; bj < 2; ++bj) { const f32x4 v0 = acc[ai][bj][m][0] * sc, v1 = acc[ai][bj][m][1] * sc; const int col = col0 + bj * HALF;
;                     u32x4 w; w.x = pk_bf16(v0[0], v0[1]); w.y = pk_bf16(v0[2], v0[3]); w.z = pk_bf16(v1[0], v1[1]); w.w = pk_bf16(v1[2], v1[3]);
;                     bf16_t* dst;
;                     if (u.kind == 0) {
;                         const int isk = col >> 9, c = col & 511, rr = isk ? pi32e(row & 31) : (row & 31);
;                         dst = base + (size_t)isk * ((size_t)T * 512) + ((((size_t)(row >> 5) * 8 + (c >> 6)) * 4 + ((c & 63) >> 4)) * 64 + ((c >> 3) & 1) * 32 + rr) * 8;
;                     } else if (u.kind == 1) {
;                         dst = base + ((((size_t)(col >> 5) * 8 + (row >> 6)) * 4 + ((row & 63) >> 5) * 2 + ((col & 31) >> 4)) * 64 + ((col >> 3) & 1) * 32 + (row & 31)) * 8;
;                     } else dst = base + (size_t)row * ldc + col;
;                     *(u32x4*)dst = w; } }
.LBB0_192:
	v_mov_b32_e32 v124, v150
	v_mov_b32_e32 v125, v150
	v_pk_mul_f32 v[118:119], v[124:125], v[118:119]
	v_pk_mul_f32 v[116:117], v[150:151], v[116:117]
	v_pk_mul_f32 v[124:125], v[124:125], v[114:115]
	v_pk_mul_f32 v[114:115], v[150:151], v[112:113]
	v_cvt_pk_bf16_f32 v112, v116, v117
	v_cvt_pk_bf16_f32 v113, v118, v119
	v_cvt_pk_bf16_f32 v114, v114, v115
	v_cvt_pk_bf16_f32 v115, v124, v125
	s_mov_b64 s[72:73], -1
	s_mov_b64 s[54:55], 0
	s_cmp_lt_i32 s38, 1
	s_mov_b64 s[62:63], 0
	s_cselect_b32 s32, 1, 0
	s_cmp_eq_u32 s38, 2
	s_cbranch_scc1 .Lk2b_0
	s_cmp_lg_u32 s32, 0
	global_store_dwordx4 v[120:121], v[112:115], off
	s_branch .Lk2d_0
.Lk2b_0:
	s_nop 1
	v_mov_b32_dpp v240, v112 row_ror:8 row_mask:0xf bank_mask:0xf
	v_mov_b32_dpp v241, v113 row_ror:8 row_mask:0xf bank_mask:0xf
	v_mov_b32_dpp v242, v114 row_ror:8 row_mask:0xf bank_mask:0xf
	v_mov_b32_dpp v243, v115 row_ror:8 row_mask:0xf bank_mask:0xf
	v_mov_b32_dpp v244, v236 row_ror:8 row_mask:0xf bank_mask:0xf
	v_mov_b32_dpp v245, v237 row_ror:8 row_mask:0xf bank_mask:0xf
	v_mov_b32_dpp v246, v238 row_ror:8 row_mask:0xf bank_mask:0xf
	v_mov_b32_dpp v247, v239 row_ror:8 row_mask:0xf bank_mask:0xf
	v_cndmask_b32_e64 v236, v236, v240, s[100:101]
	v_cndmask_b32_e64 v237, v237, v241, s[100:101]
	v_cndmask_b32_e64 v238, v238, v242, s[100:101]
	v_cndmask_b32_e64 v239, v239, v243, s[100:101]
	v_cndmask_b32_e64 v244, v244, v112, s[100:101]
	v_cndmask_b32_e64 v245, v245, v113, s[100:101]
	v_cndmask_b32_e64 v246, v246, v114, s[100:101]
	v_cndmask_b32_e64 v247, v247, v115, s[100:101]
	v_lshl_add_u64 v[252:253], v[120:121], 0, v[248:249]
	v_lshl_add_u64 v[254:255], v[120:121], 0, v[250:251]
	global_store_dwordx4 v[252:253], v[236:239], off
	global_store_dwordx4 v[254:255], v[244:247], off
	s_cmp_lg_u32 s32, 0
.Lk2d_0:
	s_cbranch_scc1 .LBB0_196
	s_cmp_eq_u32 s38, 1
	s_mov_b64 s[62:63], -1
	s_cbranch_scc0 .LBB0_195
	s_ashr_i32 s62, s36, 5
	s_ashr_i32 s63, s62, 31
	s_lshl_b64 s[62:63], s[62:63], 11
	v_lshlrev_b64 v[112:113], 6, v[154:155]
	v_lshl_add_u64 v[112:113], v[112:113], 0, s[62:63]
	v_or_b32_e32 v112, v112, v144
	v_lshl_add_u64 v[114:115], v[112:113], 4, s[30:31]
	s_mov_b64 s[62:63], 0

; DI unsigned pk_bf16(float lo, float hi) { f32x2 v = {lo, hi}; bf2_t b = __builtin_convertvector(v, bf2_t); return __builtin_bit_cast(unsigned, b); }
; DI int pi32e(int r) { return (r & ~12) | ((r & 4) << 1) | ((r & 8) >> 1); }
;     DI void operator()(const f32x4 (&acc)[2][2][4][2], const Unit& u, int wr, int wc, int fr, int fq) const {
;     ...
;                 for (int bj = 0; bj < 2; ++bj) { const f32x4 v0 = acc[ai][bj][m][0] * sc, v1 = acc[ai][bj][m][1] * sc; const int col = col0 + bj * HALF;
;                     u32x4 w; w.x = pk_bf16(v0[0], v0[1]); w.y = pk_bf16(v0[2], v0[3]); w.z = pk_bf16(v1[0], v1[1]); w.w = pk_bf16(v1[2], v1[3]);
;                     bf16_t* dst;
;                     if (u.kind == 0) {
;                         const int isk = col >> 9, c = col & 511, rr = isk ? pi32e(row & 31) : (row & 31);
;                         dst = base + (size_t)isk * ((size_t)T * 512) + ((((size_t)(row >> 5) * 8 + (c >> 6)) * 4 + ((c & 63) >> 4)) * 64 + ((c >> 3) & 1) * 32 + rr) * 8;
;                     } else if (u.kind == 1) {
;                         dst = base + ((((size_t)(col >> 5) * 8 + (row >> 6)) * 4 + ((row & 63) >> 5) * 2 + ((col & 31) >> 4)) * 64 + ((col >> 3) & 1) * 32 + (row & 31)) * 8;
;                     } else dst = base + (size_t)row * ldc + col;
;                     *(u32x4*)dst = w; } }
.LBB0_202:
	v_mov_b32_e32 v118, v150
	v_mov_b32_e32 v119, v150
	v_pk_mul_f32 v[110:111], v[118:119], v[110:111]
	v_pk_mul_f32 v[108:109], v[150:151], v[108:109]
	v_pk_mul_f32 v[118:119], v[118:119], v[106:107]
	v_pk_mul_f32 v[106:107], v[150:151], v[104:105]
	v_cvt_pk_bf16_f32 v104, v108, v109
	v_cvt_pk_bf16_f32 v105, v110, v111
	v_cvt_pk_bf16_f32 v106, v106, v107
	v_cvt_pk_bf16_f32 v107, v118, v119
	s_mov_b64 s[72:73], -1
	s_mov_b64 s[54:55], 0
	s_cmp_lt_i32 s38, 1
	s_mov_b64 s[62:63], 0
	s_cselect_b32 s32, 1, 0
	s_cmp_eq_u32 s38, 2
	s_cbranch_scc1 .Lk2a_1
	s_cmp_lg_u32 s32, 0
	global_store_dwordx4 v[114:115], v[104:107], off
	s_branch .Lk2c_1
.Lk2a_1:
	v_mov_b32_e32 v236, v104
	v_mov_b32_e32 v237, v105
	v_mov_b32_e32 v238, v106
	v_mov_b32_e32 v239, v107
	s_cmp_lg_u32 s32, 0

; DI unsigned pk_bf16(float lo, float hi) { f32x2 v = {lo, hi}; bf2_t b = __builtin_convertvector(v, bf2_t); return __builtin_bit_cast(unsigned, b); }
; DI int pi32e(int r) { return (r & ~12) | ((r & 4) << 1) | ((r & 8) >> 1); }
;     DI void operator()(const f32x4 (&acc)[2][2][4][2], const Unit& u, int wr, int wc, int fr, int fq) const {
;     ...
;                 for (int bj = 0; bj < 2; ++bj) { const f32x4 v0 = acc[ai][bj][m][0] * sc, v1 = acc[ai][bj][m][1] * sc; const int col = col0 + bj * HALF;
;                     u32x4 w; w.x = pk_bf16(v0[0], v0[1]); w.y = pk_bf16(v0[2], v0[3]); w.z = pk_bf16(v1[0], v1[1]); w.w = pk_bf16(v1[2], v1[3]);
;                     bf16_t* dst;
;                     if (u.kind == 0) {
;                         const int isk = col >> 9, c = col & 511, rr = isk ? pi32e(row & 31) : (row & 31);
;                         dst = base + (size_t)isk * ((size_t)T * 512) + ((((size_t)(row >> 5) * 8 + (c >> 6)) * 4 + ((c & 63) >> 4)) * 64 + ((c >> 3) & 1) * 32 + rr) * 8;
;                     } else if (u.kind == 1) {
;                         dst = base + ((((size_t)(col >> 5) * 8 + (row >> 6)) * 4 + ((row & 63) >> 5) * 2 + ((col & 31) >> 4)) * 64 + ((col >> 3) & 1) * 32 + (row & 31)) * 8;
;                     } else dst = base + (size_t)row * ldc + col;
;                     *(u32x4*)dst = w; } }
.LBB0_207:
	v_mov_b32_e32 v106, v150
	v_mov_b32_e32 v107, v150
	v_pk_mul_f32 v[102:103], v[106:107], v[102:103]
	v_pk_mul_f32 v[100:101], v[150:151], v[100:101]
	v_pk_mul_f32 v[106:107], v[106:107], v[98:99]
	v_pk_mul_f32 v[98:99], v[150:151], v[96:97]
	v_cvt_pk_bf16_f32 v96, v100, v101
	v_cvt_pk_bf16_f32 v97, v102, v103
	v_cvt_pk_bf16_f32 v98, v98, v99
	v_cvt_pk_bf16_f32 v99, v106, v107
	v_or_b32_e32 v154, 2, v154
	s_mov_b64 s[72:73], -1
	s_mov_b64 s[54:55], 0
	s_cmp_lt_i32 s38, 1
	s_mov_b64 s[62:63], 0
	s_cselect_b32 s32, 1, 0
	s_cmp_eq_u32 s38, 2
	s_cbranch_scc1 .Lk2b_1
	s_cmp_lg_u32 s32, 0
	global_store_dwordx4 v[104:105], v[96:99], off
	s_branch .Lk2d_1
.Lk2b_1:
	s_nop 1
	v_mov_b32_dpp v240, v96 row_ror:8 row_mask:0xf bank_mask:0xf
	v_mov_b32_dpp v241, v97 row_ror:8 row_mask:0xf bank_mask:0xf
	v_mov_b32_dpp v242, v98 row_ror:8 row_mask:0xf bank_mask:0xf
	v_mov_b32_dpp v243, v99 row_ror:8 row_mask:0xf bank_mask:0xf
	v_mov_b32_dpp v244, v236 row_ror:8 row_mask:0xf bank_mask:0xf
	v_mov_b32_dpp v245, v237 row_ror:8 row_mask:0xf bank_mask:0xf
	v_mov_b32_dpp v246, v238 row_ror:8 row_mask:0xf bank_mask:0xf
	v_mov_b32_dpp v247, v239 row_ror:8 row_mask:0xf bank_mask:0xf
	v_cndmask_b32_e64 v236, v236, v240, s[100:101]
	v_cndmask_b32_e64 v237, v237, v241, s[100:101]
	v_cndmask_b32_e64 v238, v238, v242, s[100:101]
	v_cndmask_b32_e64 v239, v239, v243, s[100:101]
	v_cndmask_b32_e64 v244, v244, v96, s[100:101]
	v_cndmask_b32_e64 v245, v245, v97, s[100:101]
	v_cndmask_b32_e64 v246, v246, v98, s[100:101]
	v_cndmask_b32_e64 v247, v247, v99, s[100:101]
	v_lshl_add_u64 v[252:253], v[104:105], 0, v[248:249]
	v_lshl_add_u64 v[254:255], v[104:105], 0, v[250:251]
	global_store_dwordx4 v[252:253], v[236:239], off
	global_store_dwordx4 v[254:255], v[244:247], off
	s_cmp_lg_u32 s32, 0
.Lk2d_1:
	s_cbranch_scc1 .LBB0_211
	s_cmp_eq_u32 s38, 1
	s_mov_b64 s[62:63], -1
	s_cbranch_scc0 .LBB0_210
	s_ashr_i32 s62, s36, 5
	s_ashr_i32 s63, s62, 31
	s_lshl_b64 s[62:63], s[62:63], 11
	v_lshlrev_b64 v[96:97], 6, v[154:155]
	v_lshl_add_u64 v[96:97], v[96:97], 0, s[62:63]
	v_or_b32_e32 v96, v96, v142
	v_lshl_add_u64 v[100:101], v[96:97], 4, s[30:31]
	s_mov_b64 s[62:63], 0

; DI unsigned pk_bf16(float lo, float hi) { f32x2 v = {lo, hi}; bf2_t b = __builtin_convertvector(v, bf2_t); return __builtin_bit_cast(unsigned, b); }
; DI int pi32e(int r) { return (r & ~12) | ((r & 4) << 1) | ((r & 8) >> 1); }
;     DI void operator()(const f32x4 (&acc)[2][2][4][2], const Unit& u, int wr, int wc, int fr, int fq) const {
;     ...
;                 for (int bj = 0; bj < 2; ++bj) { const f32x4 v0 = acc[ai][bj][m][0] * sc, v1 = acc[ai][bj][m][1] * sc; const int col = col0 + bj * HALF;
;                     u32x4 w; w.x = pk_bf16(v0[0], v0[1]); w.y = pk_bf16(v0[2], v0[3]); w.z = pk_bf16(v1[0], v1[1]); w.w = pk_bf16(v1[2], v1[3]);
;                     bf16_t* dst;
;                     if (u.kind == 0) {
;                         const int isk = col >> 9, c = col & 511, rr = isk ? pi32e(row & 31) : (row & 31);
;                         dst = base + (size_t)isk * ((size_t)T * 512) + ((((size_t)(row >> 5) * 8 + (c >> 6)) * 4 + ((c & 63) >> 4)) * 64 + ((c >> 3) & 1) * 32 + rr) * 8;
;                     } else if (u.kind == 1) {
;                         dst = base + ((((size_t)(col >> 5) * 8 + (row >> 6)) * 4 + ((row & 63) >> 5) * 2 + ((col & 31) >> 4)) * 64 + ((col >> 3) & 1) * 32 + (row & 31)) * 8;
;                     } else dst = base + (size_t)row * ldc + col;
;                     *(u32x4*)dst = w; } }
.LBB0_217:
	v_mov_b32_e32 v102, v150
	v_mov_b32_e32 v103, v150
	v_pk_mul_f32 v[94:95], v[102:103], v[94:95]
	v_pk_mul_f32 v[92:93], v[150:151], v[92:93]
	v_pk_mul_f32 v[102:103], v[102:103], v[90:91]
	v_pk_mul_f32 v[90:91], v[150:151], v[88:89]
	v_cvt_pk_bf16_f32 v88, v92, v93
	v_cvt_pk_bf16_f32 v89, v94, v95
	v_cvt_pk_bf16_f32 v90, v90, v91
	v_cvt_pk_bf16_f32 v91, v102, v103
	s_mov_b64 s[72:73], -1
	s_mov_b64 s[54:55], 0
	s_cmp_lt_i32 s38, 1
	s_mov_b64 s[62:63], 0
	s_cselect_b32 s32, 1, 0
	s_cmp_eq_u32 s38, 2
	s_cbranch_scc1 .Lk2a_2
	s_cmp_lg_u32 s32, 0
	global_store_dwordx4 v[100:101], v[88:91], off
	s_branch .Lk2c_2
.Lk2a_2:
	v_mov_b32_e32 v236, v88
	v_mov_b32_e32 v237, v89
	v_mov_b32_e32 v238, v90
	v_mov_b32_e32 v239, v91
	s_cmp_lg_u32 s32, 0

; DI unsigned pk_bf16(float lo, float hi) { f32x2 v = {lo, hi}; bf2_t b = __builtin_convertvector(v, bf2_t); return __builtin_bit_cast(unsigned, b); }
; DI int pi32e(int r) { return (r & ~12) | ((r & 4) << 1) | ((r & 8) >> 1); }
;     DI void operator()(const f32x4 (&acc)[2][2][4][2], const Unit& u, int wr, int wc, int fr, int fq) const {
;     ...
;                 for (int bj = 0; bj < 2; ++bj) { const f32x4 v0 = acc[ai][bj][m][0] * sc, v1 = acc[ai][bj][m][1] * sc; const int col = col0 + bj * HALF;
;                     u32x4 w; w.x = pk_bf16(v0[0], v0[1]); w.y = pk_bf16(v0[2], v0[3]); w.z = pk_bf16(v1[0], v1[1]); w.w = pk_bf16(v1[2], v1[3]);
;                     bf16_t* dst;
;                     if (u.kind == 0) {
;                         const int isk = col >> 9, c = col & 511, rr = isk ? pi32e(row & 31) : (row & 31);
;                         dst = base + (size_t)isk * ((size_t)T * 512) + ((((size_t)(row >> 5) * 8 + (c >> 6)) * 4 + ((c & 63) >> 4)) * 64 + ((c >> 3) & 1) * 32 + rr) * 8;
;                     } else if (u.kind == 1) {
;                         dst = base + ((((size_t)(col >> 5) * 8 + (row >> 6)) * 4 + ((row & 63) >> 5) * 2 + ((col & 31) >> 4)) * 64 + ((col >> 3) & 1) * 32 + (row & 31)) * 8;
;                     } else dst = base + (size_t)row * ldc + col;
;                     *(u32x4*)dst = w; } }
.LBB0_222:
	v_mov_b32_e32 v90, v150
	v_mov_b32_e32 v91, v150
	v_pk_mul_f32 v[86:87], v[90:91], v[86:87]
	v_pk_mul_f32 v[84:85], v[150:151], v[84:85]
	v_pk_mul_f32 v[90:91], v[90:91], v[82:83]
	v_pk_mul_f32 v[82:83], v[150:151], v[80:81]
	v_cvt_pk_bf16_f32 v80, v84, v85
	v_cvt_pk_bf16_f32 v81, v86, v87
	v_cvt_pk_bf16_f32 v82, v82, v83
	v_cvt_pk_bf16_f32 v83, v90, v91
	s_mov_b64 s[72:73], -1
	s_mov_b64 s[54:55], 0
	s_cmp_lt_i32 s38, 1
	s_mov_b64 s[62:63], 0
	s_cselect_b32 s32, 1, 0
	s_cmp_eq_u32 s38, 2
	s_cbranch_scc1 .Lk2b_2
	s_cmp_lg_u32 s32, 0
	global_store_dwordx4 v[88:89], v[80:83], off
	s_branch .Lk2d_2
.Lk2b_2:
	s_nop 1
	v_mov_b32_dpp v240, v80 row_ror:8 row_mask:0xf bank_mask:0xf
	v_mov_b32_dpp v241, v81 row_ror:8 row_mask:0xf bank_mask:0xf
	v_mov_b32_dpp v242, v82 row_ror:8 row_mask:0xf bank_mask:0xf
	v_mov_b32_dpp v243, v83 row_ror:8 row_mask:0xf bank_mask:0xf
	v_mov_b32_dpp v244, v236 row_ror:8 row_mask:0xf bank_mask:0xf
	v_mov_b32_dpp v245, v237 row_ror:8 row_mask:0xf bank_mask:0xf
	v_mov_b32_dpp v246, v238 row_ror:8 row_mask:0xf bank_mask:0xf
	v_mov_b32_dpp v247, v239 row_ror:8 row_mask:0xf bank_mask:0xf
	v_cndmask_b32_e64 v236, v236, v240, s[100:101]
	v_cndmask_b32_e64 v237, v237, v241, s[100:101]
	v_cndmask_b32_e64 v238, v238, v242, s[100:101]
	v_cndmask_b32_e64 v239, v239, v243, s[100:101]
	v_cndmask_b32_e64 v244, v244, v80, s[100:101]
	v_cndmask_b32_e64 v245, v245, v81, s[100:101]
	v_cndmask_b32_e64 v246, v246, v82, s[100:101]
	v_cndmask_b32_e64 v247, v247, v83, s[100:101]
	v_lshl_add_u64 v[252:253], v[88:89], 0, v[248:249]
	v_lshl_add_u64 v[254:255], v[88:89], 0, v[250:251]
	global_store_dwordx4 v[252:253], v[236:239], off
	global_store_dwordx4 v[254:255], v[244:247], off
	s_cmp_lg_u32 s32, 0
.Lk2d_2:
	s_cbranch_scc1 .LBB0_226
	s_cmp_eq_u32 s38, 1
	s_mov_b64 s[62:63], -1
	s_cbranch_scc0 .LBB0_225
	s_ashr_i32 s62, s36, 5
	s_ashr_i32 s63, s62, 31
	s_lshl_b64 s[62:63], s[62:63], 11
	v_lshlrev_b64 v[80:81], 6, v[154:155]
	v_lshl_add_u64 v[80:81], v[80:81], 0, s[62:63]
	v_or_b32_e32 v80, v80, v144
	v_lshl_add_u64 v[84:85], v[80:81], 4, s[30:31]
	s_mov_b64 s[62:63], 0

; DI unsigned pk_bf16(float lo, float hi) { f32x2 v = {lo, hi}; bf2_t b = __builtin_convertvector(v, bf2_t); return __builtin_bit_cast(unsigned, b); }
; DI int pi32e(int r) { return (r & ~12) | ((r & 4) << 1) | ((r & 8) >> 1); }
;     DI void operator()(const f32x4 (&acc)[2][2][4][2], const Unit& u, int wr, int wc, int fr, int fq) const {
;     ...
;                 for (int bj = 0; bj < 2; ++bj) { const f32x4 v0 = acc[ai][bj][m][0] * sc, v1 = acc[ai][bj][m][1] * sc; const int col = col0 + bj * HALF;
;                     u32x4 w; w.x = pk_bf16(v0[0], v0[1]); w.y = pk_bf16(v0[2], v0[3]); w.z = pk_bf16(v1[0], v1[1]); w.w = pk_bf16(v1[2], v1[3]);
;                     bf16_t* dst;
;                     if (u.kind == 0) {
;                         const int isk = col >> 9, c = col & 511, rr = isk ? pi32e(row & 31) : (row & 31);
;                         dst = base + (size_t)isk * ((size_t)T * 512) + ((((size_t)(row >> 5) * 8 + (c >> 6)) * 4 + ((c & 63) >> 4)) * 64 + ((c >> 3) & 1) * 32 + rr) * 8;
;                     } else if (u.kind == 1) {
;                         dst = base + ((((size_t)(col >> 5) * 8 + (row >> 6)) * 4 + ((row & 63) >> 5) * 2 + ((col & 31) >> 4)) * 64 + ((col >> 3) & 1) * 32 + (row & 31)) * 8;
;                     } else dst = base + (size_t)row * ldc + col;
;                     *(u32x4*)dst = w; } }
.LBB0_232:
	v_mov_b32_e32 v88, v150
	v_mov_b32_e32 v89, v150
	v_pk_mul_f32 v[78:79], v[88:89], v[78:79]
	v_pk_mul_f32 v[76:77], v[150:151], v[76:77]
	v_pk_mul_f32 v[88:89], v[88:89], v[74:75]
	v_pk_mul_f32 v[74:75], v[150:151], v[72:73]
	v_cvt_pk_bf16_f32 v72, v76, v77
	v_cvt_pk_bf16_f32 v73, v78, v79
	v_cvt_pk_bf16_f32 v74, v74, v75
	v_cvt_pk_bf16_f32 v75, v88, v89
	s_mov_b64 s[72:73], -1
	s_mov_b64 s[54:55], 0
	s_cmp_lt_i32 s38, 1
	s_mov_b64 s[62:63], 0
	s_cselect_b32 s32, 1, 0
	s_cmp_eq_u32 s38, 2
	s_cbranch_scc1 .Lk2a_3
	s_cmp_lg_u32 s32, 0
	global_store_dwordx4 v[84:85], v[72:75], off
	s_branch .Lk2c_3
.Lk2a_3:
	v_mov_b32_e32 v236, v72
	v_mov_b32_e32 v237, v73
	v_mov_b32_e32 v238, v74
	v_mov_b32_e32 v239, v75
	s_cmp_lg_u32 s32, 0

; DI unsigned pk_bf16(float lo, float hi) { f32x2 v = {lo, hi}; bf2_t b = __builtin_convertvector(v, bf2_t); return __builtin_bit_cast(unsigned, b); }
; DI int pi32e(int r) { return (r & ~12) | ((r & 4) << 1) | ((r & 8) >> 1); }
;     DI void operator()(const f32x4 (&acc)[2][2][4][2], const Unit& u, int wr, int wc, int fr, int fq) const {
;     ...
;             for (int m = 0; m < 4; ++m) { const int row = row0 + ai * HALF + m * 16;
; #pragma unroll
;                 for (int bj = 0; bj < 2; ++bj) { const f32x4 v0 = acc[ai][bj][m][0] * sc, v1 = acc[ai][bj][m][1] * sc; const int col = col0 + bj * HALF;
;                     u32x4 w; w.x = pk_bf16(v0[0], v0[1]); w.y = pk_bf16(v0[2], v0[3]); w.z = pk_bf16(v1[0], v1[1]); w.w = pk_bf16(v1[2], v1[3]);
;                     bf16_t* dst;
;                     if (u.kind == 0) {
;                         const int isk = col >> 9, c = col & 511, rr = isk ? pi32e(row & 31) : (row & 31);
;                         dst = base + (size_t)isk * ((size_t)T * 512) + ((((size_t)(row >> 5) * 8 + (c >> 6)) * 4 + ((c & 63) >> 4)) * 64 + ((c >> 3) & 1) * 32 + rr) * 8;
;                     } else if (u.kind == 1) {
;                         dst = base + ((((size_t)(col >> 5) * 8 + (row >> 6)) * 4 + ((row & 63) >> 5) * 2 + ((col & 31) >> 4)) * 64 + ((col >> 3) & 1) * 32 + (row & 31)) * 8;
;                     } else dst = base + (size_t)row * ldc + col;
;                     *(u32x4*)dst = w; } }
.LBB0_237:
	v_mov_b32_e32 v74, v150
	v_mov_b32_e32 v75, v150
	v_pk_mul_f32 v[70:71], v[74:75], v[70:71]
	v_pk_mul_f32 v[68:69], v[150:151], v[68:69]
	v_pk_mul_f32 v[74:75], v[74:75], v[66:67]
	v_pk_mul_f32 v[66:67], v[150:151], v[64:65]
	v_cvt_pk_bf16_f32 v64, v68, v69
	v_cvt_pk_bf16_f32 v65, v70, v71
	v_cvt_pk_bf16_f32 v66, v66, v67
	v_cvt_pk_bf16_f32 v67, v74, v75
	v_add_u32_e32 v68, 0x80, v168
	s_cselect_b32 s32, 1, 0
	s_cmp_eq_u32 s38, 2
	s_cbranch_scc1 .Lk2b_3
	s_cmp_lg_u32 s32, 0
	global_store_dwordx4 v[72:73], v[64:67], off
	s_branch .Lk2d_3
.Lk2b_3:
	s_nop 1
	v_mov_b32_dpp v240, v64 row_ror:8 row_mask:0xf bank_mask:0xf
	v_mov_b32_dpp v241, v65 row_ror:8 row_mask:0xf bank_mask:0xf
	v_mov_b32_dpp v242, v66 row_ror:8 row_mask:0xf bank_mask:0xf
	v_mov_b32_dpp v243, v67 row_ror:8 row_mask:0xf bank_mask:0xf
	v_mov_b32_dpp v244, v236 row_ror:8 row_mask:0xf bank_mask:0xf
	v_mov_b32_dpp v245, v237 row_ror:8 row_mask:0xf bank_mask:0xf
	v_mov_b32_dpp v246, v238 row_ror:8 row_mask:0xf bank_mask:0xf
	v_mov_b32_dpp v247, v239 row_ror:8 row_mask:0xf bank_mask:0xf
	v_cndmask_b32_e64 v236, v236, v240, s[100:101]
	v_cndmask_b32_e64 v237, v237, v241, s[100:101]
	v_cndmask_b32_e64 v238, v238, v242, s[100:101]
	v_cndmask_b32_e64 v239, v239, v243, s[100:101]
	v_cndmask_b32_e64 v244, v244, v64, s[100:101]
	v_cndmask_b32_e64 v245, v245, v65, s[100:101]
	v_cndmask_b32_e64 v246, v246, v66, s[100:101]
	v_cndmask_b32_e64 v247, v247, v67, s[100:101]
	v_lshl_add_u64 v[252:253], v[72:73], 0, v[248:249]
	v_lshl_add_u64 v[254:255], v[72:73], 0, v[250:251]
	global_store_dwordx4 v[252:253], v[236:239], off
	global_store_dwordx4 v[254:255], v[244:247], off
	s_cmp_lg_u32 s32, 0
.Lk2d_3:
	s_mov_b64 s[72:73], -1
	s_mov_b64 s[54:55], 0
	v_ashrrev_i32_e32 v64, 6, v68
	v_ashrrev_i32_e32 v65, 31, v64
	v_lshlrev_b64 v[64:65], 2, v[64:65]
	v_or_b32_e32 v64, v64, v138
	s_cmp_lt_i32 s38, 1
	s_mov_b64 s[62:63], 0
	s_cbranch_scc1 .LBB0_241
	s_cmp_eq_u32 s38, 1
	s_mov_b64 s[62:63], -1
	s_cbranch_scc0 .LBB0_240
	s_ashr_i32 s62, s36, 5
	s_ashr_i32 s63, s62, 31
	s_lshl_b64 s[62:63], s[62:63], 11
	v_lshlrev_b64 v[66:67], 6, v[64:65]
	v_lshl_add_u64 v[66:67], v[66:67], 0, s[62:63]
	v_or_b32_e32 v66, v66, v142
	v_lshl_add_u64 v[70:71], v[66:67], 4, s[30:31]
	s_mov_b64 s[62:63], 0

; DI unsigned pk_bf16(float lo, float hi) { f32x2 v = {lo, hi}; bf2_t b = __builtin_convertvector(v, bf2_t); return __builtin_bit_cast(unsigned, b); }
; DI int pi32e(int r) { return (r & ~12) | ((r & 4) << 1) | ((r & 8) >> 1); }
;     DI void operator()(const f32x4 (&acc)[2][2][4][2], const Unit& u, int wr, int wc, int fr, int fq) const {
;     ...
;                 for (int bj = 0; bj < 2; ++bj) { const f32x4 v0 = acc[ai][bj][m][0] * sc, v1 = acc[ai][bj][m][1] * sc; const int col = col0 + bj * HALF;
;                     u32x4 w; w.x = pk_bf16(v0[0], v0[1]); w.y = pk_bf16(v0[2], v0[3]); w.z = pk_bf16(v1[0], v1[1]); w.w = pk_bf16(v1[2], v1[3]);
;                     bf16_t* dst;
;                     if (u.kind == 0) {
;                         const int isk = col >> 9, c = col & 511, rr = isk ? pi32e(row & 31) : (row & 31);
;                         dst = base + (size_t)isk * ((size_t)T * 512) + ((((size_t)(row >> 5) * 8 + (c >> 6)) * 4 + ((c & 63) >> 4)) * 64 + ((c >> 3) & 1) * 32 + rr) * 8;
;                     } else if (u.kind == 1) {
;                         dst = base + ((((size_t)(col >> 5) * 8 + (row >> 6)) * 4 + ((row & 63) >> 5) * 2 + ((col & 31) >> 4)) * 64 + ((col >> 3) & 1) * 32 + (row & 31)) * 8;
;                     } else dst = base + (size_t)row * ldc + col;
;                     *(u32x4*)dst = w; } }
.LBB0_247:
	v_mov_b32_e32 v72, v150
	v_mov_b32_e32 v73, v150
	v_pk_mul_f32 v[62:63], v[72:73], v[62:63]
	v_pk_mul_f32 v[60:61], v[150:151], v[60:61]
	v_pk_mul_f32 v[72:73], v[72:73], v[58:59]
	v_pk_mul_f32 v[58:59], v[150:151], v[56:57]
	v_cvt_pk_bf16_f32 v56, v60, v61
	v_cvt_pk_bf16_f32 v57, v62, v63
	v_cvt_pk_bf16_f32 v58, v58, v59
	v_cvt_pk_bf16_f32 v59, v72, v73
	s_mov_b64 s[72:73], -1
	s_mov_b64 s[54:55], 0
	s_cmp_lt_i32 s38, 1
	s_mov_b64 s[62:63], 0
	s_cselect_b32 s32, 1, 0
	s_cmp_eq_u32 s38, 2
	s_cbranch_scc1 .Lk2a_4
	s_cmp_lg_u32 s32, 0
	global_store_dwordx4 v[70:71], v[56:59], off
	s_branch .Lk2c_4
.Lk2a_4:
	v_mov_b32_e32 v236, v56
	v_mov_b32_e32 v237, v57
	v_mov_b32_e32 v238, v58
	v_mov_b32_e32 v239, v59
	s_cmp_lg_u32 s32, 0

; DI unsigned pk_bf16(float lo, float hi) { f32x2 v = {lo, hi}; bf2_t b = __builtin_convertvector(v, bf2_t); return __builtin_bit_cast(unsigned, b); }
; DI int pi32e(int r) { return (r & ~12) | ((r & 4) << 1) | ((r & 8) >> 1); }
;     DI void operator()(const f32x4 (&acc)[2][2][4][2], const Unit& u, int wr, int wc, int fr, int fq) const {
;     ...
;                 for (int bj = 0; bj < 2; ++bj) { const f32x4 v0 = acc[ai][bj][m][0] * sc, v1 = acc[ai][bj][m][1] * sc; const int col = col0 + bj * HALF;
;                     u32x4 w; w.x = pk_bf16(v0[0], v0[1]); w.y = pk_bf16(v0[2], v0[3]); w.z = pk_bf16(v1[0], v1[1]); w.w = pk_bf16(v1[2], v1[3]);
;                     bf16_t* dst;
;                     if (u.kind == 0) {
;                         const int isk = col >> 9, c = col & 511, rr = isk ? pi32e(row & 31) : (row & 31);
;                         dst = base + (size_t)isk * ((size_t)T * 512) + ((((size_t)(row >> 5) * 8 + (c >> 6)) * 4 + ((c & 63) >> 4)) * 64 + ((c >> 3) & 1) * 32 + rr) * 8;
;                     } else if (u.kind == 1) {
;                         dst = base + ((((size_t)(col >> 5) * 8 + (row >> 6)) * 4 + ((row & 63) >> 5) * 2 + ((col & 31) >> 4)) * 64 + ((col >> 3) & 1) * 32 + (row & 31)) * 8;
;                     } else dst = base + (size_t)row * ldc + col;
;                     *(u32x4*)dst = w; } }
.LBB0_252:
	v_mov_b32_e32 v58, v150
	v_mov_b32_e32 v59, v150
	v_pk_mul_f32 v[54:55], v[58:59], v[54:55]
	v_pk_mul_f32 v[52:53], v[150:151], v[52:53]
	v_pk_mul_f32 v[58:59], v[58:59], v[50:51]
	v_pk_mul_f32 v[50:51], v[150:151], v[48:49]
	v_cvt_pk_bf16_f32 v48, v52, v53
	v_cvt_pk_bf16_f32 v49, v54, v55
	v_cvt_pk_bf16_f32 v50, v50, v51
	v_cvt_pk_bf16_f32 v51, v58, v59
	s_mov_b64 s[72:73], -1
	s_mov_b64 s[54:55], 0
	s_cmp_lt_i32 s38, 1
	s_mov_b64 s[62:63], 0
	s_cselect_b32 s32, 1, 0
	s_cmp_eq_u32 s38, 2
	s_cbranch_scc1 .Lk2b_4
	s_cmp_lg_u32 s32, 0
	global_store_dwordx4 v[56:57], v[48:51], off
	s_branch .Lk2d_4
.Lk2b_4:
	s_nop 1
	v_mov_b32_dpp v240, v48 row_ror:8 row_mask:0xf bank_mask:0xf
	v_mov_b32_dpp v241, v49 row_ror:8 row_mask:0xf bank_mask:0xf
	v_mov_b32_dpp v242, v50 row_ror:8 row_mask:0xf bank_mask:0xf
	v_mov_b32_dpp v243, v51 row_ror:8 row_mask:0xf bank_mask:0xf
	v_mov_b32_dpp v244, v236 row_ror:8 row_mask:0xf bank_mask:0xf
	v_mov_b32_dpp v245, v237 row_ror:8 row_mask:0xf bank_mask:0xf
	v_mov_b32_dpp v246, v238 row_ror:8 row_mask:0xf bank_mask:0xf
	v_mov_b32_dpp v247, v239 row_ror:8 row_mask:0xf bank_mask:0xf
	v_cndmask_b32_e64 v236, v236, v240, s[100:101]
	v_cndmask_b32_e64 v237, v237, v241, s[100:101]
	v_cndmask_b32_e64 v238, v238, v242, s[100:101]
	v_cndmask_b32_e64 v239, v239, v243, s[100:101]
	v_cndmask_b32_e64 v244, v244, v48, s[100:101]
	v_cndmask_b32_e64 v245, v245, v49, s[100:101]
	v_cndmask_b32_e64 v246, v246, v50, s[100:101]
	v_cndmask_b32_e64 v247, v247, v51, s[100:101]
	v_lshl_add_u64 v[252:253], v[56:57], 0, v[248:249]
	v_lshl_add_u64 v[254:255], v[56:57], 0, v[250:251]
	global_store_dwordx4 v[252:253], v[236:239], off
	global_store_dwordx4 v[254:255], v[244:247], off
	s_cmp_lg_u32 s32, 0
.Lk2d_4:
	s_cbranch_scc1 .LBB0_256
	s_cmp_eq_u32 s38, 1
	s_mov_b64 s[62:63], -1
	s_cbranch_scc0 .LBB0_255
	s_ashr_i32 s62, s36, 5
	s_ashr_i32 s63, s62, 31
	s_lshl_b64 s[62:63], s[62:63], 11
	v_lshlrev_b64 v[48:49], 6, v[64:65]
	v_lshl_add_u64 v[48:49], v[48:49], 0, s[62:63]
	v_or_b32_e32 v48, v48, v144
	v_lshl_add_u64 v[52:53], v[48:49], 4, s[30:31]
	s_mov_b64 s[62:63], 0

; DI unsigned pk_bf16(float lo, float hi) { f32x2 v = {lo, hi}; bf2_t b = __builtin_convertvector(v, bf2_t); return __builtin_bit_cast(unsigned, b); }
; DI int pi32e(int r) { return (r & ~12) | ((r & 4) << 1) | ((r & 8) >> 1); }
;     DI void operator()(const f32x4 (&acc)[2][2][4][2], const Unit& u, int wr, int wc, int fr, int fq) const {
;     ...
;                 for (int bj = 0; bj < 2; ++bj) { const f32x4 v0 = acc[ai][bj][m][0] * sc, v1 = acc[ai][bj][m][1] * sc; const int col = col0 + bj * HALF;
;                     u32x4 w; w.x = pk_bf16(v0[0], v0[1]); w.y = pk_bf16(v0[2], v0[3]); w.z = pk_bf16(v1[0], v1[1]); w.w = pk_bf16(v1[2], v1[3]);
;                     bf16_t* dst;
;                     if (u.kind == 0) {
;                         const int isk = col >> 9, c = col & 511, rr = isk ? pi32e(row & 31) : (row & 31);
;                         dst = base + (size_t)isk * ((size_t)T * 512) + ((((size_t)(row >> 5) * 8 + (c >> 6)) * 4 + ((c & 63) >> 4)) * 64 + ((c >> 3) & 1) * 32 + rr) * 8;
;                     } else if (u.kind == 1) {
;                         dst = base + ((((size_t)(col >> 5) * 8 + (row >> 6)) * 4 + ((row & 63) >> 5) * 2 + ((col & 31) >> 4)) * 64 + ((col >> 3) & 1) * 32 + (row & 31)) * 8;
;                     } else dst = base + (size_t)row * ldc + col;
;                     *(u32x4*)dst = w; } }
.LBB0_262:
	v_mov_b32_e32 v56, v150
	v_mov_b32_e32 v57, v150
	v_pk_mul_f32 v[46:47], v[56:57], v[46:47]
	v_pk_mul_f32 v[44:45], v[150:151], v[44:45]
	v_pk_mul_f32 v[56:57], v[56:57], v[42:43]
	v_pk_mul_f32 v[42:43], v[150:151], v[40:41]
	v_cvt_pk_bf16_f32 v40, v44, v45
	v_cvt_pk_bf16_f32 v41, v46, v47
	v_cvt_pk_bf16_f32 v42, v42, v43
	v_cvt_pk_bf16_f32 v43, v56, v57
	s_mov_b64 s[72:73], -1
	s_mov_b64 s[54:55], 0
	s_cmp_lt_i32 s38, 1
	s_mov_b64 s[62:63], 0
	s_cselect_b32 s32, 1, 0
	s_cmp_eq_u32 s38, 2
	s_cbranch_scc1 .Lk2a_5
	s_cmp_lg_u32 s32, 0
	global_store_dwordx4 v[52:53], v[40:43], off
	s_branch .Lk2c_5
.Lk2a_5:
	v_mov_b32_e32 v236, v40
	v_mov_b32_e32 v237, v41
	v_mov_b32_e32 v238, v42
	v_mov_b32_e32 v239, v43
	s_cmp_lg_u32 s32, 0

; DI unsigned pk_bf16(float lo, float hi) { f32x2 v = {lo, hi}; bf2_t b = __builtin_convertvector(v, bf2_t); return __builtin_bit_cast(unsigned, b); }
; DI int pi32e(int r) { return (r & ~12) | ((r & 4) << 1) | ((r & 8) >> 1); }
;     DI void operator()(const f32x4 (&acc)[2][2][4][2], const Unit& u, int wr, int wc, int fr, int fq) const {
;     ...
;                 for (int bj = 0; bj < 2; ++bj) { const f32x4 v0 = acc[ai][bj][m][0] * sc, v1 = acc[ai][bj][m][1] * sc; const int col = col0 + bj * HALF;
;                     u32x4 w; w.x = pk_bf16(v0[0], v0[1]); w.y = pk_bf16(v0[2], v0[3]); w.z = pk_bf16(v1[0], v1[1]); w.w = pk_bf16(v1[2], v1[3]);
;                     bf16_t* dst;
;                     if (u.kind == 0) {
;                         const int isk = col >> 9, c = col & 511, rr = isk ? pi32e(row & 31) : (row & 31);
;                         dst = base + (size_t)isk * ((size_t)T * 512) + ((((size_t)(row >> 5) * 8 + (c >> 6)) * 4 + ((c & 63) >> 4)) * 64 + ((c >> 3) & 1) * 32 + rr) * 8;
;                     } else if (u.kind == 1) {
;                         dst = base + ((((size_t)(col >> 5) * 8 + (row >> 6)) * 4 + ((row & 63) >> 5) * 2 + ((col & 31) >> 4)) * 64 + ((col >> 3) & 1) * 32 + (row & 31)) * 8;
;                     } else dst = base + (size_t)row * ldc + col;
;                     *(u32x4*)dst = w; } }
.LBB0_267:
	v_mov_b32_e32 v42, v150
	v_mov_b32_e32 v43, v150
	v_pk_mul_f32 v[38:39], v[42:43], v[38:39]
	v_pk_mul_f32 v[36:37], v[150:151], v[36:37]
	v_pk_mul_f32 v[42:43], v[42:43], v[34:35]
	v_pk_mul_f32 v[34:35], v[150:151], v[32:33]
	v_cvt_pk_bf16_f32 v32, v36, v37
	v_cvt_pk_bf16_f32 v33, v38, v39
	v_cvt_pk_bf16_f32 v34, v34, v35
	v_cvt_pk_bf16_f32 v35, v42, v43
	v_or_b32_e32 v64, 2, v64
	s_mov_b64 s[72:73], -1
	s_mov_b64 s[54:55], 0
	s_cmp_lt_i32 s38, 1
	s_mov_b64 s[62:63], 0
	s_cselect_b32 s32, 1, 0
	s_cmp_eq_u32 s38, 2
	s_cbranch_scc1 .Lk2b_5
	s_cmp_lg_u32 s32, 0
	global_store_dwordx4 v[40:41], v[32:35], off
	s_branch .Lk2d_5
.Lk2b_5:
	s_nop 1
	v_mov_b32_dpp v240, v32 row_ror:8 row_mask:0xf bank_mask:0xf
	v_mov_b32_dpp v241, v33 row_ror:8 row_mask:0xf bank_mask:0xf
	v_mov_b32_dpp v242, v34 row_ror:8 row_mask:0xf bank_mask:0xf
	v_mov_b32_dpp v243, v35 row_ror:8 row_mask:0xf bank_mask:0xf
	v_mov_b32_dpp v244, v236 row_ror:8 row_mask:0xf bank_mask:0xf
	v_mov_b32_dpp v245, v237 row_ror:8 row_mask:0xf bank_mask:0xf
	v_mov_b32_dpp v246, v238 row_ror:8 row_mask:0xf bank_mask:0xf
	v_mov_b32_dpp v247, v239 row_ror:8 row_mask:0xf bank_mask:0xf
	v_cndmask_b32_e64 v236, v236, v240, s[100:101]
	v_cndmask_b32_e64 v237, v237, v241, s[100:101]
	v_cndmask_b32_e64 v238, v238, v242, s[100:101]
	v_cndmask_b32_e64 v239, v239, v243, s[100:101]
	v_cndmask_b32_e64 v244, v244, v32, s[100:101]
	v_cndmask_b32_e64 v245, v245, v33, s[100:101]
	v_cndmask_b32_e64 v246, v246, v34, s[100:101]
	v_cndmask_b32_e64 v247, v247, v35, s[100:101]
	v_lshl_add_u64 v[252:253], v[40:41], 0, v[248:249]
	v_lshl_add_u64 v[254:255], v[40:41], 0, v[250:251]
	global_store_dwordx4 v[252:253], v[236:239], off
	global_store_dwordx4 v[254:255], v[244:247], off
	s_cmp_lg_u32 s32, 0
.Lk2d_5:
	s_cbranch_scc1 .LBB0_271
	s_cmp_eq_u32 s38, 1
	s_mov_b64 s[62:63], -1
	s_cbranch_scc0 .LBB0_270
	s_ashr_i32 s62, s36, 5
	s_ashr_i32 s63, s62, 31
	s_lshl_b64 s[62:63], s[62:63], 11
	v_lshlrev_b64 v[32:33], 6, v[64:65]
	v_lshl_add_u64 v[32:33], v[32:33], 0, s[62:63]
	v_or_b32_e32 v32, v32, v142
	v_lshl_add_u64 v[36:37], v[32:33], 4, s[30:31]
	s_mov_b64 s[62:63], 0

; DI unsigned pk_bf16(float lo, float hi) { f32x2 v = {lo, hi}; bf2_t b = __builtin_convertvector(v, bf2_t); return __builtin_bit_cast(unsigned, b); }
; DI int pi32e(int r) { return (r & ~12) | ((r & 4) << 1) | ((r & 8) >> 1); }
;     DI void operator()(const f32x4 (&acc)[2][2][4][2], const Unit& u, int wr, int wc, int fr, int fq) const {
;     ...
;                 for (int bj = 0; bj < 2; ++bj) { const f32x4 v0 = acc[ai][bj][m][0] * sc, v1 = acc[ai][bj][m][1] * sc; const int col = col0 + bj * HALF;
;                     u32x4 w; w.x = pk_bf16(v0[0], v0[1]); w.y = pk_bf16(v0[2], v0[3]); w.z = pk_bf16(v1[0], v1[1]); w.w = pk_bf16(v1[2], v1[3]);
;                     bf16_t* dst;
;                     if (u.kind == 0) {
;                         const int isk = col >> 9, c = col & 511, rr = isk ? pi32e(row & 31) : (row & 31);
;                         dst = base + (size_t)isk * ((size_t)T * 512) + ((((size_t)(row >> 5) * 8 + (c >> 6)) * 4 + ((c & 63) >> 4)) * 64 + ((c >> 3) & 1) * 32 + rr) * 8;
;                     } else if (u.kind == 1) {
;                         dst = base + ((((size_t)(col >> 5) * 8 + (row >> 6)) * 4 + ((row & 63) >> 5) * 2 + ((col & 31) >> 4)) * 64 + ((col >> 3) & 1) * 32 + (row & 31)) * 8;
;                     } else dst = base + (size_t)row * ldc + col;
;                     *(u32x4*)dst = w; } }
.LBB0_277:
	v_mov_b32_e32 v38, v150
	v_mov_b32_e32 v39, v150
	v_pk_mul_f32 v[30:31], v[38:39], v[30:31]
	v_pk_mul_f32 v[28:29], v[150:151], v[28:29]
	v_pk_mul_f32 v[38:39], v[38:39], v[26:27]
	v_pk_mul_f32 v[26:27], v[150:151], v[24:25]
	v_cvt_pk_bf16_f32 v24, v28, v29
	v_cvt_pk_bf16_f32 v25, v30, v31
	v_cvt_pk_bf16_f32 v26, v26, v27
	v_cvt_pk_bf16_f32 v27, v38, v39
	s_mov_b64 s[72:73], -1
	s_mov_b64 s[54:55], 0
	s_cmp_lt_i32 s38, 1
	s_mov_b64 s[62:63], 0
	s_cselect_b32 s32, 1, 0
	s_cmp_eq_u32 s38, 2
	s_cbranch_scc1 .Lk2a_6
	s_cmp_lg_u32 s32, 0
	global_store_dwordx4 v[36:37], v[24:27], off
	s_branch .Lk2c_6
.Lk2a_6:
	v_mov_b32_e32 v236, v24
	v_mov_b32_e32 v237, v25
	v_mov_b32_e32 v238, v26
	v_mov_b32_e32 v239, v27
	s_cmp_lg_u32 s32, 0

; DI unsigned pk_bf16(float lo, float hi) { f32x2 v = {lo, hi}; bf2_t b = __builtin_convertvector(v, bf2_t); return __builtin_bit_cast(unsigned, b); }
; DI int pi32e(int r) { return (r & ~12) | ((r & 4) << 1) | ((r & 8) >> 1); }
;     DI void operator()(const f32x4 (&acc)[2][2][4][2], const Unit& u, int wr, int wc, int fr, int fq) const {
;     ...
;                 for (int bj = 0; bj < 2; ++bj) { const f32x4 v0 = acc[ai][bj][m][0] * sc, v1 = acc[ai][bj][m][1] * sc; const int col = col0 + bj * HALF;
;                     u32x4 w; w.x = pk_bf16(v0[0], v0[1]); w.y = pk_bf16(v0[2], v0[3]); w.z = pk_bf16(v1[0], v1[1]); w.w = pk_bf16(v1[2], v1[3]);
;                     bf16_t* dst;
;                     if (u.kind == 0) {
;                         const int isk = col >> 9, c = col & 511, rr = isk ? pi32e(row & 31) : (row & 31);
;                         dst = base + (size_t)isk * ((size_t)T * 512) + ((((size_t)(row >> 5) * 8 + (c >> 6)) * 4 + ((c & 63) >> 4)) * 64 + ((c >> 3) & 1) * 32 + rr) * 8;
;                     } else if (u.kind == 1) {
;                         dst = base + ((((size_t)(col >> 5) * 8 + (row >> 6)) * 4 + ((row & 63) >> 5) * 2 + ((col & 31) >> 4)) * 64 + ((col >> 3) & 1) * 32 + (row & 31)) * 8;
;                     } else dst = base + (size_t)row * ldc + col;
;                     *(u32x4*)dst = w; } }
.LBB0_282:
	v_mov_b32_e32 v26, v150
	v_mov_b32_e32 v27, v150
	v_pk_mul_f32 v[22:23], v[26:27], v[22:23]
	v_pk_mul_f32 v[20:21], v[150:151], v[20:21]
	v_pk_mul_f32 v[26:27], v[26:27], v[18:19]
	v_pk_mul_f32 v[18:19], v[150:151], v[16:17]
	v_cvt_pk_bf16_f32 v16, v20, v21
	v_cvt_pk_bf16_f32 v17, v22, v23
	v_cvt_pk_bf16_f32 v18, v18, v19
	v_cvt_pk_bf16_f32 v19, v26, v27
	s_mov_b64 s[72:73], -1
	s_mov_b64 s[54:55], 0
	s_cmp_lt_i32 s38, 1
	s_mov_b64 s[62:63], 0
	s_cselect_b32 s32, 1, 0
	s_cmp_eq_u32 s38, 2
	s_cbranch_scc1 .Lk2b_6
	s_cmp_lg_u32 s32, 0
	global_store_dwordx4 v[24:25], v[16:19], off
	s_branch .Lk2d_6
.Lk2b_6:
	s_nop 1
	v_mov_b32_dpp v240, v16 row_ror:8 row_mask:0xf bank_mask:0xf
	v_mov_b32_dpp v241, v17 row_ror:8 row_mask:0xf bank_mask:0xf
	v_mov_b32_dpp v242, v18 row_ror:8 row_mask:0xf bank_mask:0xf
	v_mov_b32_dpp v243, v19 row_ror:8 row_mask:0xf bank_mask:0xf
	v_mov_b32_dpp v244, v236 row_ror:8 row_mask:0xf bank_mask:0xf
	v_mov_b32_dpp v245, v237 row_ror:8 row_mask:0xf bank_mask:0xf
	v_mov_b32_dpp v246, v238 row_ror:8 row_mask:0xf bank_mask:0xf
	v_mov_b32_dpp v247, v239 row_ror:8 row_mask:0xf bank_mask:0xf
	v_cndmask_b32_e64 v236, v236, v240, s[100:101]
	v_cndmask_b32_e64 v237, v237, v241, s[100:101]
	v_cndmask_b32_e64 v238, v238, v242, s[100:101]
	v_cndmask_b32_e64 v239, v239, v243, s[100:101]
	v_cndmask_b32_e64 v244, v244, v16, s[100:101]
	v_cndmask_b32_e64 v245, v245, v17, s[100:101]
	v_cndmask_b32_e64 v246, v246, v18, s[100:101]
	v_cndmask_b32_e64 v247, v247, v19, s[100:101]
	v_lshl_add_u64 v[252:253], v[24:25], 0, v[248:249]
	v_lshl_add_u64 v[254:255], v[24:25], 0, v[250:251]
	global_store_dwordx4 v[252:253], v[236:239], off
	global_store_dwordx4 v[254:255], v[244:247], off
	s_cmp_lg_u32 s32, 0
.Lk2d_6:
	s_cbranch_scc1 .LBB0_286
	s_cmp_eq_u32 s38, 1
	s_mov_b64 s[62:63], -1
	s_cbranch_scc0 .LBB0_285
	s_ashr_i32 s62, s36, 5
	s_ashr_i32 s63, s62, 31
	s_lshl_b64 s[62:63], s[62:63], 11
	v_lshlrev_b64 v[16:17], 6, v[64:65]
	v_lshl_add_u64 v[16:17], v[16:17], 0, s[62:63]
	v_or_b32_e32 v16, v16, v144
	v_lshl_add_u64 v[20:21], v[16:17], 4, s[30:31]
	s_mov_b64 s[62:63], 0

; DI unsigned pk_bf16(float lo, float hi) { f32x2 v = {lo, hi}; bf2_t b = __builtin_convertvector(v, bf2_t); return __builtin_bit_cast(unsigned, b); }
; DI int pi32e(int r) { return (r & ~12) | ((r & 4) << 1) | ((r & 8) >> 1); }
;     DI void operator()(const f32x4 (&acc)[2][2][4][2], const Unit& u, int wr, int wc, int fr, int fq) const {
;     ...
;                 for (int bj = 0; bj < 2; ++bj) { const f32x4 v0 = acc[ai][bj][m][0] * sc, v1 = acc[ai][bj][m][1] * sc; const int col = col0 + bj * HALF;
;                     u32x4 w; w.x = pk_bf16(v0[0], v0[1]); w.y = pk_bf16(v0[2], v0[3]); w.z = pk_bf16(v1[0], v1[1]); w.w = pk_bf16(v1[2], v1[3]);
;                     bf16_t* dst;
;                     if (u.kind == 0) {
;                         const int isk = col >> 9, c = col & 511, rr = isk ? pi32e(row & 31) : (row & 31);
;                         dst = base + (size_t)isk * ((size_t)T * 512) + ((((size_t)(row >> 5) * 8 + (c >> 6)) * 4 + ((c & 63) >> 4)) * 64 + ((c >> 3) & 1) * 32 + rr) * 8;
;                     } else if (u.kind == 1) {
;                         dst = base + ((((size_t)(col >> 5) * 8 + (row >> 6)) * 4 + ((row & 63) >> 5) * 2 + ((col & 31) >> 4)) * 64 + ((col >> 3) & 1) * 32 + (row & 31)) * 8;
;                     } else dst = base + (size_t)row * ldc + col;
;                     *(u32x4*)dst = w; } }
.LBB0_292:
	v_mov_b32_e32 v24, v150
	v_mov_b32_e32 v25, v150
	v_pk_mul_f32 v[14:15], v[24:25], v[14:15]
	v_pk_mul_f32 v[12:13], v[150:151], v[12:13]
	v_pk_mul_f32 v[24:25], v[24:25], v[10:11]
	v_pk_mul_f32 v[10:11], v[150:151], v[8:9]
	v_cvt_pk_bf16_f32 v8, v12, v13
	v_cvt_pk_bf16_f32 v9, v14, v15
	v_cvt_pk_bf16_f32 v10, v10, v11
	v_cvt_pk_bf16_f32 v11, v24, v25
	s_mov_b64 s[54:55], -1
	s_mov_b64 s[0:1], 0
	s_cmp_lt_i32 s38, 1
	s_mov_b64 s[52:53], 0
	s_cselect_b32 s32, 1, 0
	s_cmp_eq_u32 s38, 2
	s_cbranch_scc1 .Lk2a_7
	s_cmp_lg_u32 s32, 0
	global_store_dwordx4 v[20:21], v[8:11], off
	s_branch .Lk2c_7
.Lk2a_7:
	v_mov_b32_e32 v236, v8
	v_mov_b32_e32 v237, v9
	v_mov_b32_e32 v238, v10
	v_mov_b32_e32 v239, v11
	s_cmp_lg_u32 s32, 0
.Lk2c_7:
	s_cbranch_scc0 .LBB0_335
	s_and_b64 vcc, exec, s[54:55]
	s_cbranch_vccnz .LBB0_338

; DI unsigned pk_bf16(float lo, float hi) { f32x2 v = {lo, hi}; bf2_t b = __builtin_convertvector(v, bf2_t); return __builtin_bit_cast(unsigned, b); }
; DI int pi32e(int r) { return (r & ~12) | ((r & 4) << 1) | ((r & 8) >> 1); }
;     DI void operator()(const f32x4 (&acc)[2][2][4][2], const Unit& u, int wr, int wc, int fr, int fq) const {
;     ...
;                 for (int bj = 0; bj < 2; ++bj) { const f32x4 v0 = acc[ai][bj][m][0] * sc, v1 = acc[ai][bj][m][1] * sc; const int col = col0 + bj * HALF;
;                     u32x4 w; w.x = pk_bf16(v0[0], v0[1]); w.y = pk_bf16(v0[2], v0[3]); w.z = pk_bf16(v1[0], v1[1]); w.w = pk_bf16(v1[2], v1[3]);
;                     bf16_t* dst;
;                     if (u.kind == 0) {
;                         const int isk = col >> 9, c = col & 511, rr = isk ? pi32e(row & 31) : (row & 31);
;                         dst = base + (size_t)isk * ((size_t)T * 512) + ((((size_t)(row >> 5) * 8 + (c >> 6)) * 4 + ((c & 63) >> 4)) * 64 + ((c >> 3) & 1) * 32 + rr) * 8;
;                     } else if (u.kind == 1) {
;                         dst = base + ((((size_t)(col >> 5) * 8 + (row >> 6)) * 4 + ((row & 63) >> 5) * 2 + ((col & 31) >> 4)) * 64 + ((col >> 3) & 1) * 32 + (row & 31)) * 8;
;                     } else dst = base + (size_t)row * ldc + col;
;                     *(u32x4*)dst = w; } }
; template <class Epi, class Sched, bool ALIGN_EPI = false, bool SP2 = true>
; DI void gemm_phase(LAS unsigned char* lds, const Gemm g, const Sched& S, const Epi& E, f32x4 (&acc)[2][2][4][2]) {
;     ...
;         if (!has_next) break;
; #pragma unroll
;         for (int a = 0; a < 2; ++a)
; #pragma unroll
;             for (int b = 0; b < 2; ++b)
; #pragma unroll
;                 for (int m = 0; m < 4; ++m)
; #pragma unroll
;                     for (int n = 0; n < 2; ++n) acc[a][b][m][n] = (f32x4){0.f, 0.f, 0.f, 0.f};
;         cur = nxt; cA = nA; cB = nB; ++ui;
.LBB0_297:
	v_mov_b32_e32 v10, v150
	v_mov_b32_e32 v11, v150
	v_pk_mul_f32 v[6:7], v[10:11], v[6:7]
	v_pk_mul_f32 v[4:5], v[150:151], v[4:5]
	v_pk_mul_f32 v[2:3], v[10:11], v[2:3]
	v_pk_mul_f32 v[0:1], v[150:151], v[0:1]
	v_cvt_pk_bf16_f32 v4, v4, v5
	v_cvt_pk_bf16_f32 v5, v6, v7
	v_cvt_pk_bf16_f32 v6, v0, v1
	v_cvt_pk_bf16_f32 v7, v2, v3
	s_andn2_b64 vcc, exec, s[20:21]
	s_mov_b64 s[0:1], -1
	s_cselect_b32 s32, 1, 0
	s_cmp_eq_u32 s38, 2
	s_cbranch_scc1 .Lk2b_7
	s_cmp_lg_u32 s32, 0
	global_store_dwordx4 v[8:9], v[4:7], off
	s_branch .Lk2d_7
.Lk2b_7:
	s_nop 1
	v_mov_b32_dpp v240, v4 row_ror:8 row_mask:0xf bank_mask:0xf
	v_mov_b32_dpp v241, v5 row_ror:8 row_mask:0xf bank_mask:0xf
	v_mov_b32_dpp v242, v6 row_ror:8 row_mask:0xf bank_mask:0xf
	v_mov_b32_dpp v243, v7 row_ror:8 row_mask:0xf bank_mask:0xf
	v_mov_b32_dpp v244, v236 row_ror:8 row_mask:0xf bank_mask:0xf
	v_mov_b32_dpp v245, v237 row_ror:8 row_mask:0xf bank_mask:0xf
	v_mov_b32_dpp v246, v238 row_ror:8 row_mask:0xf bank_mask:0xf
	v_mov_b32_dpp v247, v239 row_ror:8 row_mask:0xf bank_mask:0xf
	v_cndmask_b32_e64 v236, v236, v240, s[100:101]
	v_cndmask_b32_e64 v237, v237, v241, s[100:101]
	v_cndmask_b32_e64 v238, v238, v242, s[100:101]
	v_cndmask_b32_e64 v239, v239, v243, s[100:101]
	v_cndmask_b32_e64 v244, v244, v4, s[100:101]
	v_cndmask_b32_e64 v245, v245, v5, s[100:101]
	v_cndmask_b32_e64 v246, v246, v6, s[100:101]
	v_cndmask_b32_e64 v247, v247, v7, s[100:101]
	v_lshl_add_u64 v[252:253], v[8:9], 0, v[248:249]
	v_lshl_add_u64 v[254:255], v[8:9], 0, v[250:251]
	global_store_dwordx4 v[252:253], v[236:239], off
	global_store_dwordx4 v[254:255], v[244:247], off
	s_cmp_lg_u32 s32, 0
.Lk2d_7:
	s_cbranch_vccnz .LBB0_142
	s_andn2_b64 vcc, exec, s[12:13]
	s_cbranch_vccnz .LBB0_141
	s_barrier
	s_branch .LBB0_141

; template <int PH> __global__ void __launch_bounds__(512, 2) fwd(Params p) {
	.amdhsa_kernel _Z3fwdILin1EEv6Params
		.amdhsa_group_segment_fixed_size 0
		.amdhsa_private_segment_fixed_size 0
		.amdhsa_kernarg_size 376
		.amdhsa_user_sgpr_count 2
		.amdhsa_user_sgpr_dispatch_ptr 0
		.amdhsa_user_sgpr_queue_ptr 0
		.amdhsa_user_sgpr_kernarg_segment_ptr 1
		.amdhsa_user_sgpr_dispatch_id 0
		.amdhsa_user_sgpr_kernarg_preload_length 0
		.amdhsa_user_sgpr_kernarg_preload_offset 0
		.amdhsa_user_sgpr_private_segment_size 0
		.amdhsa_uses_dynamic_stack 0
		.amdhsa_enable_private_segment 0
		.amdhsa_system_sgpr_workgroup_id_x 1
		.amdhsa_system_sgpr_workgroup_id_y 0
		.amdhsa_system_sgpr_workgroup_id_z 0
		.amdhsa_system_sgpr_workgroup_info 0
		.amdhsa_system_vgpr_workitem_id 2
		.amdhsa_next_free_vgpr 256
		.amdhsa_next_free_sgpr 102
		.amdhsa_accum_offset 256
		.amdhsa_reserve_vcc 1
		.amdhsa_float_round_mode_32 0
		.amdhsa_float_round_mode_16_64 0
		.amdhsa_float_denorm_mode_32 3
		.amdhsa_float_denorm_mode_16_64 3
		.amdhsa_dx10_clamp 1
		.amdhsa_ieee_mode 1
		.amdhsa_fp16_overflow 0
		.amdhsa_tg_split 0
		.amdhsa_exception_fp_ieee_invalid_op 0
		.amdhsa_exception_fp_denorm_src 0
		.amdhsa_exception_fp_ieee_div_zero 0
		.amdhsa_exception_fp_ieee_overflow 0
		.amdhsa_exception_fp_ieee_underflow 0
		.amdhsa_exception_fp_ieee_inexact 0
		.amdhsa_exception_int_div_zero 0
	.end_amdhsa_kernel

; template <int PH> __global__ void __launch_bounds__(512, 2) fwd(Params p) {
amdhsa.kernels:
  - .agpr_count:     0
    .args:
      - .offset:         0
        .size:           120
        .value_kind:     by_value
      - .offset:         120
        .size:           4
        .value_kind:     hidden_block_count_x
      - .offset:         124
        .size:           4
        .value_kind:     hidden_block_count_y
      - .offset:         128
        .size:           4
        .value_kind:     hidden_block_count_z
      - .offset:         132
        .size:           2
        .value_kind:     hidden_group_size_x
      - .offset:         134
        .size:           2
        .value_kind:     hidden_group_size_y
      - .offset:         136
        .size:           2
        .value_kind:     hidden_group_size_z
      - .offset:         138
        .size:           2
        .value_kind:     hidden_remainder_x
      - .offset:         140
        .size:           2
        .value_kind:     hidden_remainder_y
      - .offset:         142
        .size:           2
        .value_kind:     hidden_remainder_z
      - .offset:         160
        .size:           8
        .value_kind:     hidden_global_offset_x
      - .offset:         168
        .size:           8
        .value_kind:     hidden_global_offset_y
      - .offset:         176
        .size:           8
        .value_kind:     hidden_global_offset_z
      - .offset:         184
        .size:           2
        .value_kind:     hidden_grid_dims
      - .offset:         208
        .size:           8
        .value_kind:     hidden_multigrid_sync_arg
      - .offset:         240
        .size:           4
        .value_kind:     hidden_dynamic_lds_size
    .group_segment_fixed_size: 0
    .kernarg_segment_align: 8
    .kernarg_segment_size: 376
    .language:       OpenCL C
    .language_version:
      - 2
      - 0
    .max_flat_workgroup_size: 512
    .name:           _Z3fwdILin1EEv6Params
    .private_segment_fixed_size: 0
    .sgpr_count:     108
    .sgpr_spill_count: 4
    .symbol:         _Z3fwdILin1EEv6Params.kd
    .uniform_work_group_size: 1
    .uses_dynamic_stack: false
    .vgpr_count:     256
    .vgpr_spill_count: 0
    .wavefront_size: 64
  - .agpr_count:     0
    .args:
      - .offset:         0
        .size:           120
        .value_kind:     by_value
      - .offset:         120
        .size:           4
        .value_kind:     hidden_block_count_x
      - .offset:         124
        .size:           4
        .value_kind:     hidden_block_count_y
      - .offset:         128
        .size:           4
        .value_kind:     hidden_block_count_z
      - .offset:         132
        .size:           2
        .value_kind:     hidden_group_size_x
      - .offset:         134
        .size:           2
        .value_kind:     hidden_group_size_y
      - .offset:         136
        .size:           2
        .value_kind:     hidden_group_size_z
      - .offset:         138
        .size:           2
        .value_kind:     hidden_remainder_x
      - .offset:         140
        .size:           2
        .value_kind:     hidden_remainder_y
      - .offset:         142
        .size:           2
        .value_kind:     hidden_remainder_z
      - .offset:         160
        .size:           8
        .value_kind:     hidden_global_offset_x
      - .offset:         168
        .size:           8
        .value_kind:     hidden_global_offset_y
      - .offset:         176
        .size:           8
        .value_kind:     hidden_global_offset_z
      - .offset:         184
        .size:           2
        .value_kind:     hidden_grid_dims
      - .offset:         240
        .size:           4
        .value_kind:     hidden_dynamic_lds_size
    .group_segment_fixed_size: 0
    .kernarg_segment_align: 8
    .kernarg_segment_size: 376
    .language:       OpenCL C
    .language_version:
      - 2
      - 0
    .max_flat_workgroup_size: 512
    .name:           _Z3fwdILi0EEv6Params
    .private_segment_fixed_size: 0
    .sgpr_count:     59
    .sgpr_spill_count: 0
    .symbol:         _Z3fwdILi0EEv6Params.kd
    .uniform_work_group_size: 1
    .uses_dynamic_stack: false
    .vgpr_count:     76
    .vgpr_spill_count: 0
    .wavefront_size: 64
  - .agpr_count:     0
    .args:
      - .offset:         0
        .size:           120
        .value_kind:     by_value
      - .offset:         120
        .size:           4
        .value_kind:     hidden_block_count_x
      - .offset:         124
        .size:           4
        .value_kind:     hidden_block_count_y
      - .offset:         128
        .size:           4
        .value_kind:     hidden_block_count_z
      - .offset:         132
        .size:           2
        .value_kind:     hidden_group_size_x
      - .offset:         134
        .size:           2
        .value_kind:     hidden_group_size_y
      - .offset:         136
        .size:           2
        .value_kind:     hidden_group_size_z
      - .offset:         138
        .size:           2
        .value_kind:     hidden_remainder_x
      - .offset:         140
        .size:           2
        .value_kind:     hidden_remainder_y
      - .offset:         142
        .size:           2
        .value_kind:     hidden_remainder_z
      - .offset:         160
        .size:           8
        .value_kind:     hidden_global_offset_x
      - .offset:         168
        .size:           8
        .value_kind:     hidden_global_offset_y
      - .offset:         176
        .size:           8
        .value_kind:     hidden_global_offset_z
      - .offset:         184
        .size:           2
        .value_kind:     hidden_grid_dims
      - .offset:         240
        .size:           4
        .value_kind:     hidden_dynamic_lds_size
    .group_segment_fixed_size: 0
    .kernarg_segment_align: 8
    .kernarg_segment_size: 376
    .language:       OpenCL C
    .language_version:
      - 2
      - 0
    .max_flat_workgroup_size: 512
    .name:           _Z3fwdILi1EEv6Params
    .private_segment_fixed_size: 0
    .sgpr_count:     70
    .sgpr_spill_count: 0
    .symbol:         _Z3fwdILi1EEv6Params.kd
    .uniform_work_group_size: 1
    .uses_dynamic_stack: false
    .vgpr_count:     230
    .vgpr_spill_count: 0
    .wavefront_size: 64
; template <int PH> __global__ void __launch_bounds__(512, 2) fwd(Params p) {
  - .agpr_count:     0
    .args:
      - .offset:         0
        .size:           120
        .value_kind:     by_value
      - .offset:         120
        .size:           4
        .value_kind:     hidden_block_count_x
      - .offset:         124
        .size:           4
        .value_kind:     hidden_block_count_y
      - .offset:         128
        .size:           4
        .value_kind:     hidden_block_count_z
      - .offset:         132
        .size:           2
        .value_kind:     hidden_group_size_x
      - .offset:         134
        .size:           2
        .value_kind:     hidden_group_size_y
      - .offset:         136
        .size:           2
        .value_kind:     hidden_group_size_z
      - .offset:         138
        .size:           2
        .value_kind:     hidden_remainder_x
      - .offset:         140
        .size:           2
        .value_kind:     hidden_remainder_y
      - .offset:         142
        .size:           2
        .value_kind:     hidden_remainder_z
      - .offset:         160
        .size:           8
        .value_kind:     hidden_global_offset_x
      - .offset:         168
        .size:           8
        .value_kind:     hidden_global_offset_y
      - .offset:         176
        .size:           8
        .value_kind:     hidden_global_offset_z
      - .offset:         184
        .size:           2
        .value_kind:     hidden_grid_dims
      - .offset:         240
        .size:           4
        .value_kind:     hidden_dynamic_lds_size
    .group_segment_fixed_size: 0
    .kernarg_segment_align: 8
    .kernarg_segment_size: 376
    .language:       OpenCL C
    .language_version:
      - 2
      - 0
    .max_flat_workgroup_size: 512
    .name:           _Z3fwdILi2EEv6Params
    .private_segment_fixed_size: 0
    .sgpr_count:     106
    .sgpr_spill_count: 0
    .symbol:         _Z3fwdILi2EEv6Params.kd
    .uniform_work_group_size: 1
    .uses_dynamic_stack: false
    .vgpr_count:     230
    .vgpr_spill_count: 0
    .wavefront_size: 64
  - .agpr_count:     0
    .args:
      - .offset:         0
        .size:           120
        .value_kind:     by_value
      - .offset:         120
        .size:           4
        .value_kind:     hidden_block_count_x
      - .offset:         124
        .size:           4
        .value_kind:     hidden_block_count_y
      - .offset:         128
        .size:           4
        .value_kind:     hidden_block_count_z
      - .offset:         132
        .size:           2
        .value_kind:     hidden_group_size_x
      - .offset:         134
        .size:           2
        .value_kind:     hidden_group_size_y
      - .offset:         136
        .size:           2
        .value_kind:     hidden_group_size_z
      - .offset:         138
        .size:           2
        .value_kind:     hidden_remainder_x
      - .offset:         140
        .size:           2
        .value_kind:     hidden_remainder_y
      - .offset:         142
        .size:           2
        .value_kind:     hidden_remainder_z
      - .offset:         160
        .size:           8
        .value_kind:     hidden_global_offset_x
      - .offset:         168
        .size:           8
        .value_kind:     hidden_global_offset_y
      - .offset:         176
        .size:           8
        .value_kind:     hidden_global_offset_z
      - .offset:         184
        .size:           2
        .value_kind:     hidden_grid_dims
      - .offset:         240
        .size:           4
        .value_kind:     hidden_dynamic_lds_size
    .group_segment_fixed_size: 0
    .kernarg_segment_align: 8
    .kernarg_segment_size: 376
    .language:       OpenCL C
    .language_version:
      - 2
      - 0
    .max_flat_workgroup_size: 512
    .name:           _Z3fwdILi3EEv6Params
    .private_segment_fixed_size: 0
    .sgpr_count:     72
    .sgpr_spill_count: 0
    .symbol:         _Z3fwdILi3EEv6Params.kd
    .uniform_work_group_size: 1
    .uses_dynamic_stack: false
    .vgpr_count:     220
    .vgpr_spill_count: 0
    .wavefront_size: 64
  - .agpr_count:     0
    .args:
      - .offset:         0
        .size:           120
        .value_kind:     by_value
      - .offset:         120
        .size:           4
        .value_kind:     hidden_block_count_x
      - .offset:         124
        .size:           4
        .value_kind:     hidden_block_count_y
      - .offset:         128
        .size:           4
        .value_kind:     hidden_block_count_z
      - .offset:         132
        .size:           2
        .value_kind:     hidden_group_size_x
      - .offset:         134
        .size:           2
        .value_kind:     hidden_group_size_y
      - .offset:         136
        .size:           2
        .value_kind:     hidden_group_size_z
      - .offset:         138
        .size:           2
        .value_kind:     hidden_remainder_x
      - .offset:         140
        .size:           2
        .value_kind:     hidden_remainder_y
      - .offset:         142
        .size:           2
        .value_kind:     hidden_remainder_z
      - .offset:         160
        .size:           8
        .value_kind:     hidden_global_offset_x
      - .offset:         168
        .size:           8
        .value_kind:     hidden_global_offset_y
      - .offset:         176
        .size:           8
        .value_kind:     hidden_global_offset_z
      - .offset:         184
        .size:           2
        .value_kind:     hidden_grid_dims
    .group_segment_fixed_size: 0
    .kernarg_segment_align: 8
    .kernarg_segment_size: 376
    .language:       OpenCL C
    .language_version:
      - 2
      - 0
    .max_flat_workgroup_size: 512
    .name:           _Z3fwdILi4EEv6Params
    .private_segment_fixed_size: 0
    .sgpr_count:     18
    .sgpr_spill_count: 0
    .symbol:         _Z3fwdILi4EEv6Params.kd
    .uniform_work_group_size: 1
    .uses_dynamic_stack: false
    .vgpr_count:     24
    .vgpr_spill_count: 0
    .wavefront_size: 64
